# E30: P4 tail GEMM rebalanced: workgroups with 22 main units take 2 tail units (tiles 768..1023), the others 6 (tiles 0..767) instead of 0 / 8
# speedup vs baseline: 1.0063x; 1.0063x over previous
.LBB0_846:
	v_readlane_b32 s2, v251, 3
	s_abs_i32 s2, s2
	s_sub_i32 s3, 0, s2
	v_cvt_f32_u32_e32 v0, s2
	v_mbcnt_lo_u32_b32 v4, -1, 0
	v_mbcnt_hi_u32_b32 v4, -1, v4
	v_rcp_iflag_f32_e32 v0, v0
	s_nop 0
	v_mul_f32_e32 v0, 0x4f7ffffe, v0
	v_cvt_u32_f32_e32 v0, v0
	s_nop 0
	v_readfirstlane_b32 s4, v0
	s_mul_i32 s3, s3, s4
	s_mul_hi_u32 s3, s4, s3
	s_add_i32 s4, s4, s3
	s_mul_hi_u32 s3, s4, 0x1580
	s_mul_i32 s3, s3, s2
	s_sub_i32 s3, 0x1580, s3
	s_sub_i32 s4, s3, s2
	s_cmp_ge_u32 s3, s2
	s_cselect_b32 s3, s4, s3
	s_sub_i32 s4, s3, s2
	s_cmp_ge_u32 s3, s2
	s_cselect_b32 s46, s4, s3
	s_sub_i32 s47, s31, s46
	s_cmp_lt_i32 s47, 0
	s_cselect_b32 s98, 0x380, 0
	s_movk_i32 s99, 0x300
	s_cselect_b32 s99, 0x400, s99
	s_add_i32 s47, s47, s98
	s_cmpk_lt_u32 s47, 0x400
	s_cselect_b64 s[2:3], -1, 0
	s_cmpk_gt_u32 s47, 0x3ff
	s_cbranch_scc1 .LBB0_848
	s_lshl_b32 s4, s47, 3
	s_and_b32 s4, s4, 56
	s_bfe_u32 s5, s47, 0x30003
	s_or_b32 s4, s4, s5
	s_lshr_b32 s6, s47, 6

.LBB0_851:
	s_mov_b64 s[36:37], 0x80
	v_lshl_add_u64 v[6:7], v[0:1], 0, s[36:37]
	s_add_i32 m0, s14, 0x18000
	s_mov_b64 s[38:39], 0x8080
	s_waitcnt vmcnt(2)
	s_barrier
	global_load_lds_dwordx4 v[6:7], off
	v_lshl_add_u64 v[6:7], v[0:1], 0, s[38:39]
	s_add_i32 m0, s14, 0x1a000
	s_add_i32 s81, s14, 0x8000
	global_load_lds_dwordx4 v[6:7], off
	v_lshl_add_u64 v[6:7], v[2:3], 0, s[36:37]
	s_mov_b32 m0, s81
	s_add_i32 s86, s14, 0xa000
	global_load_lds_dwordx4 v[6:7], off
	v_lshl_add_u64 v[2:3], v[2:3], 0, s[38:39]
	s_mov_b32 m0, s86
	s_mov_b64 s[40:41], 0x10080
	global_load_lds_dwordx4 v[2:3], off
	v_lshl_add_u64 v[2:3], v[0:1], 0, s[40:41]
	s_add_i32 m0, s14, 0x1c000
	s_mov_b64 s[42:43], 0x18080
	global_load_lds_dwordx4 v[2:3], off
	v_lshl_add_u64 v[0:1], v[0:1], 0, s[42:43]
	s_add_i32 m0, s14, 0x1e000
	v_readlane_b32 s5, v251, 3
	global_load_lds_dwordx4 v[0:1], off
	v_and_b32_e32 v0, 15, v4
	v_or_b32_e32 v1, s68, v0
	v_lshlrev_b32_e32 v2, 6, v1
	v_and_b32_e32 v3, 48, v4
	s_movk_i32 s2, 0x3c0
	s_sub_i32 s87, s5, s46
	v_and_or_b32 v2, v2, s2, v3
	v_readlane_b32 s2, v251, 0
	s_cmpk_lt_u32 s2, 0x100
	s_cselect_b64 s[44:45], -1, 0
	s_lshl_b32 s3, s15, 2
	s_and_b32 s88, s2, 0xffffffc0
	s_lshl_b32 s2, s22, 10
	s_add_i32 s3, s3, 0
	s_add_i32 s90, s3, s2
	s_ashr_i32 s89, s87, 31
	s_add_i32 s90, s90, 0x20000
	s_ashr_i32 s2, s5, 31
	v_and_b32_e32 v5, 0xfffffc00, v5
	v_lshlrev_b32_e32 v1, 2, v1
	s_add_u32 s3, s5, s47
	v_add_u32_e32 v6, s23, v5
	v_and_b32_e32 v1, 32, v1
	v_lshl_or_b32 v0, v0, 6, v3
	v_lshlrev_b32_e32 v3, 2, v4
	s_addc_u32 s2, s2, 0
	s_ashr_i32 s5, s46, 31
	v_bitop3_b32 v1, v2, v6, v1 bitop3:0xde
	v_add_u32_e32 v2, s26, v5
	v_and_b32_e32 v3, 32, v3
	s_waitcnt vmcnt(6)
	s_sub_u32 s46, s3, s46
	v_bitop3_b32 v140, v0, v2, v3 bitop3:0xde
	s_subb_u32 s47, s2, s5
	s_add_i32 s91, 0, 0x10000
	s_add_i32 s92, 0, 0x14000
	v_mbcnt_lo_u32_b32 v0, -1, 0
	v_mov_b32_e32 v132, s99
	v_mov_b32_e32 v133, 0
	v_add_u32_e32 v134, -1, v132
	v_mov_b32_e32 v135, 0
	v_add_u32_e32 v141, s91, v140
	v_add_u32_e32 v142, s92, v140
	v_add_u32_e32 v143, 0, v1
	s_mov_b64 s[48:49], 0x100
	s_mov_b64 s[52:53], 0x8100
	s_mov_b64 s[54:55], 0x10100
	s_mov_b64 s[56:57], 0x18100
	s_mov_b64 s[58:59], 0x180
	s_mov_b64 s[60:61], 0x8180
	s_mov_b64 s[62:63], 0x10180
	s_mov_b64 s[64:65], 0x18180
	v_mbcnt_hi_u32_b32 v144, -1, v0
	s_barrier
	s_branch .LBB0_854
